# conservative compiler-inserted vmcnt(0) before the GEMM unit loop removed (prologue's counted vmcnt(6) + barrier already cover K-tile 0)
# baseline (speedup 1.0000x reference)
.LBB0_323:
	s_add_i32 m0, s9, 0x18000
	v_lshl_add_u64 v[8:9], v[8:9], 0, s[12:13]
	s_waitcnt vmcnt(2)
	s_barrier
	global_load_lds_dwordx4 v[8:9], off
	v_lshl_add_u64 v[4:5], v[4:5], 0, s[12:13]
	s_add_i32 m0, s9, 0x1a000
	s_add_i32 s77, s9, 0x8000
	global_load_lds_dwordx4 v[4:5], off
	v_lshl_add_u64 v[4:5], v[6:7], 0, s[12:13]
	s_mov_b32 m0, s77
	s_add_i32 s86, s9, 0xa000
	global_load_lds_dwordx4 v[4:5], off
	v_lshl_add_u64 v[4:5], v[10:11], 0, s[12:13]
	s_mov_b32 m0, s86
	v_lshl_add_u64 v[2:3], v[2:3], 0, s[12:13]
	global_load_lds_dwordx4 v[4:5], off
	s_add_i32 m0, s9, 0x1c000
	v_lshl_add_u64 v[0:1], v[0:1], 0, s[12:13]
	global_load_lds_dwordx4 v[2:3], off
	s_add_i32 m0, s9, 0x1e000
	s_and_b32 s48, s0, 3
	global_load_lds_dwordx4 v[0:1], off
	v_bfe_u32 v0, v12, 4, 2
	v_and_b32_e32 v1, 15, v12
	v_lshlrev_b32_e32 v3, 4, v0
	v_lshl_or_b32 v146, s1, 6, v1
	v_lshl_or_b32 v1, v1, 6, v3
	v_lshlrev_b32_e32 v3, 2, v12
	s_lshr_b32 s64, s52, 6
	s_lshl_b32 s0, s1, 13
	v_and_b32_e32 v3, 32, v3
	v_bitop3_b32 v4, v1, s0, v3 bitop3:0xde
	s_lshl_b32 s0, s48, 12
	s_add_i32 s87, s64, -2
	s_cmpk_lt_u32 s38, 0x100
	v_bitop3_b32 v147, v1, s0, v3 bitop3:0xde
	s_cselect_b64 s[0:1], -1, 0
	s_lshl_b32 s65, s50, 2
	v_cvt_f32_u32_e32 v1, s65
	v_lshlrev_b32_e32 v2, 3, v0
	v_writelane_b32 v233, s0, 50
	v_cmp_eq_u32_e64 s[38:39], 0, v0
	v_rcp_iflag_f32_e32 v0, v1
	v_writelane_b32 v233, s1, 51
	s_mov_b32 s0, s54
	s_mov_b32 s1, s47
	s_mov_b64 s[62:63], s[0:1]
	v_readlane_b32 s0, v233, 58
	s_lshr_b32 s61, s54, 3
	v_readlane_b32 s1, v233, 59
	s_and_b64 s[0:1], s[0:1], exec
	v_mul_f32_e32 v0, 0x4f7ffffe, v0
	v_readlane_b32 s0, v232, 2
	v_readlane_b32 s40, v233, 56
	v_cvt_u32_f32_e32 v0, v0
	v_readlane_b32 s1, v232, 3
	v_readlane_b32 s41, v233, 57
	s_cselect_b32 s1, s41, s1
	s_cselect_b32 s0, s40, s0
	v_writelane_b32 v232, s0, 8
	v_mov_b32_e32 v1, v97
	s_waitcnt vmcnt(6)
	s_mov_b32 s66, 0
	v_writelane_b32 v232, s1, 9
	v_readfirstlane_b32 s1, v0
	v_add_u32_e32 v0, v15, v13
	s_sub_i32 s0, 0, s65
	v_add_lshl_u32 v0, v0, v14, 1
	s_mul_i32 s0, s0, s1
	v_lshl_add_u64 v[136:137], s[34:35], 0, v[0:1]
	v_add_u32_e32 v0, v18, v16
	s_mul_hi_u32 s0, s1, s0
	v_add_lshl_u32 v0, v0, v17, 1
	s_mov_b32 s60, s48
	v_lshl_or_b32 v148, s48, 5, v2
	s_add_i32 s68, s1, s0
	v_lshl_add_u64 v[138:139], s[34:35], 0, v[0:1]
	v_add_u32_e32 v149, 0, v4
	s_barrier
	s_mov_b32 s51, 0
	v_writelane_b32 v232, s51, 60
	s_branch .LBB0_326
